# phase 4: workgroups 128..255 run their sample-row units before their five tiles (on top of the phase-1 reordering)
# speedup vs baseline: 1.0082x; 1.0082x over previous
_Z14fwd_megakernel6Params:
	s_mov_b32 s92, s2
	s_mov_b32 s100, 0
	s_mov_b32 s99, 0
	s_load_dwordx8 s[84:91], s[0:1], 0x80
	s_load_dword s2, s[0:1], 0xa0
	s_load_dwordx16 s[56:71], s[0:1], 0x0
	s_load_dwordx16 s[20:35], s[0:1], 0x40
	v_and_b32_e32 v162, 0x3ff, v0
	v_cmp_eq_u32_e64 s[4:5], 0, v162
	s_waitcnt lgkmcnt(0)
	v_writelane_b32 v251, s2, 0
	s_add_u32 s2, s0, 0x98
	s_addc_u32 s3, s1, 0
	v_writelane_b32 v251, s2, 1
	s_nop 1
	v_writelane_b32 v251, s3, 2
	s_mov_b64 s[2:3], exec
	v_writelane_b32 v251, s4, 3
	s_nop 1
	v_writelane_b32 v251, s5, 4
	s_and_b64 s[4:5], s[2:3], s[4:5]
	s_mov_b64 exec, s[4:5]
	s_cbranch_execz .LBB0_2
	v_mov_b32_e32 v2, 0
	v_mov_b32_e32 v3, v2
	v_mov_b32_e32 v4, v2
	v_mov_b32_e32 v5, v2
	v_mov_b32_e32 v1, 0x20000
	ds_write_b128 v1, v[2:5]

.LBB0_1091:
	s_add_u32 s14, s86, 0x16a0000
	s_addc_u32 s15, s87, 0
	s_add_u32 s18, s86, 0x16a5800
	s_addc_u32 s19, s87, 0
	s_add_u32 s20, s86, 0x600000
	s_addc_u32 s21, s87, 0
	v_lshrrev_b32_e32 v1, 3, v162
	v_readfirstlane_b32 s30, v162
	s_movk_i32 s0, 0x400
	v_and_b32_e32 v181, 0x70, v1
	v_and_b32_e32 v163, 15, v162
	s_cmpk_gt_i32 s92, 0x57f
	v_bfe_u32 v180, v162, 4, 2
	s_cbranch_scc1 .LBB0_1108
	s_cmp_lg_u32 s100, 0
	s_cbranch_scc1 .Lp4m_go
	s_cmpk_lt_u32 s92, 0x80
	s_cbranch_scc1 .Lp4m_go
	s_mov_b32 s100, 1
	s_branch .Lp4m_mini
.Lp4m_go:
	v_lshlrev_b32_e32 v2, 4, v162
	s_waitcnt lgkmcnt(0)
	v_add_u32_e32 v3, 0x2000, v2
	v_lshrrev_b32_e32 v3, 7, v3
	v_and_b32_e32 v4, 32, v162
	v_and_b32_e32 v14, 0xf0, v3
	v_bfe_u32 v15, v162, 2, 4
	v_bitop3_b32 v16, v2, v4, 48 bitop3:0x6c
	v_and_b32_e32 v17, 64, v162
	s_lshl_b32 s2, s0, 1
	v_or_b32_e32 v3, v14, v15
	v_or_b32_e32 v2, v16, v17
	v_mad_u64_u32 v[164:165], s[6:7], s2, v3, v[2:3]
	v_or_b32_e32 v3, v181, v15
	s_ashr_i32 s33, s92, 31
	v_mad_u64_u32 v[166:167], s[6:7], s2, v3, v[2:3]
	s_lshr_b32 s2, s33, 29
	s_add_i32 s2, s92, s2
	s_lshr_b32 s3, s30, 6
	s_ashr_i32 s1, s0, 31
	s_ashr_i32 s5, s2, 3
	s_and_b32 s2, s2, -8
	s_lshr_b32 s4, s30, 8
	s_lshl_b64 s[22:23], s[0:1], 8
	s_lshl_b64 s[24:25], s[0:1], 9
	s_lshl_b32 s31, s3, 10
	s_sub_i32 s2, s92, s2
	s_cmp_lt_i32 s2, 0
	s_movk_i32 s34, 0xb1
	s_cselect_b32 s6, s34, 0xb0
	s_mul_i32 s2, s6, s2
	s_add_i32 s2, s2, s5
	s_mul_hi_i32 s5, s2, 0x2e8ba2e9
	s_lshr_b32 s6, s5, 31
	s_ashr_i32 s5, s5, 5
	s_add_i32 s5, s5, s6
	s_lshl_b32 s6, s5, 3
	s_mulk_i32 s5, 0xb0
	s_sub_i32 s5, s2, s5
	s_sext_i32_i16 s2, s5
	s_bfe_u32 s2, s2, 0x3001c
	s_add_i32 s7, s5, s2
	s_sext_i32_i16 s26, s7
	s_and_b32 s7, s7, 0xfff8
	s_sub_i32 s5, s5, s7
	s_sext_i32_i16 s5, s5
	s_lshr_b32 s2, s26, 3
	s_add_i32 s67, s6, s5
	s_ashr_i32 s5, s67, 31
	s_bfe_i64 s[8:9], s[2:3], 0x100000
	s_mul_i32 s5, s24, s5
	s_mul_hi_u32 s6, s24, s67
	s_ashr_i32 s8, s26, 3
	s_add_i32 s5, s6, s5
	s_lshr_b64 s[6:7], s[0:1], 23
	s_mul_hi_u32 s26, s24, s8
	s_mul_i32 s9, s24, s9
	s_mul_i32 s7, s6, s67
	s_add_i32 s9, s26, s9
	s_mul_i32 s6, s6, s8
	s_add_i32 s5, s5, s7
	s_add_i32 s9, s9, s6
	s_mul_i32 s6, s24, s8
	s_add_u32 s26, s20, s6
	s_mul_i32 s7, s24, s67
	s_addc_u32 s27, s21, s9
	s_add_i32 s35, s31, 0x10000
	s_add_i32 s38, s31, 0x12000
	s_mov_b32 m0, s35
	s_add_u32 s28, s94, s7
	global_load_lds_dwordx4 v166, s[26:27]
	s_mov_b32 m0, s38
	s_addc_u32 s29, s95, s5
	s_add_i32 s39, s31, 0x2000
	global_load_lds_dwordx4 v164, s[26:27]
	s_mov_b32 m0, s31
	s_add_u32 s6, s26, s22
	global_load_lds_dwordx4 v166, s[28:29]
	s_mov_b32 m0, s39
	s_addc_u32 s7, s27, s23
	s_add_i32 s40, s31, 0x14000
	s_add_i32 s41, s31, 0x16000
	global_load_lds_dwordx4 v164, s[28:29]
	s_mov_b32 m0, s40
	s_add_u32 s8, s28, s22
	global_load_lds_dwordx4 v166, s[6:7]
	s_mov_b32 m0, s41
	s_addc_u32 s9, s29, s23
	s_add_i32 s42, s31, 0x4000
	global_load_lds_dwordx4 v164, s[6:7]
	s_mov_b32 m0, s42
	s_add_i32 s43, s31, 0x6000
	global_load_lds_dwordx4 v166, s[8:9]
	s_mov_b32 m0, s43
	v_mov_b32_e32 v167, 0
	global_load_lds_dwordx4 v164, s[8:9]
	v_mov_b32_e32 v165, v167
	s_mov_b32 s47, 0
	v_lshl_add_u64 v[12:13], s[26:27], 0, v[166:167]
	v_lshl_add_u64 v[10:11], s[26:27], 0, v[164:165]
	v_lshl_add_u64 v[8:9], s[28:29], 0, v[166:167]
	v_lshl_add_u64 v[6:7], s[28:29], 0, v[164:165]
	v_lshl_add_u64 v[4:5], s[6:7], 0, v[166:167]
	s_cmp_lg_u32 s4, 1
	v_lshl_add_u64 v[2:3], s[6:7], 0, v[164:165]
	s_cbranch_scc1 .LBB0_1094
	s_barrier

.LBB0_1108:
	s_cmp_eq_u32 s100, 2
	s_cbranch_scc1 .LBB0_1111

.LBB0_1111:
	s_cmp_lg_u32 s100, 1
	s_cbranch_scc1 .Lp4m_cont
	s_mov_b32 s100, 2
	s_waitcnt lgkmcnt(0)
	s_barrier
	s_branch .LBB0_1091
